# KV-up tile order: second KV tile of workgroups 0..127 moved to workgroups 192..255 (static rebalance of the up-proj phase)
# baseline (speedup 1.0000x reference)
.LBB0_564:
	s_mov_b64 s[26:27], s[14:15]
	s_cmp_lt_u32 s28, 0x80
	s_cbranch_scc0 .Lkv_map1
	s_add_u32 s26, s26, 0x200
	s_branch .Lkv_mapd
.Lkv_map1:
	s_cmp_lt_u32 s28, 0xc0
	s_cbranch_scc1 .Lkv_mapd
	s_sub_u32 s16, s26, 0x200
	s_cmp_lt_u32 s16, 0x100
	s_cbranch_scc0 .Lkv_map2
	s_sub_u32 s26, s26, 0x1c0
	s_branch .Lkv_mapd
.Lkv_map2:
	s_sub_u32 s16, s26, 0x300
	s_cmp_lt_u32 s16, 0x100
	s_cbranch_scc0 .Lkv_mapd
	s_sub_u32 s26, s26, 0x280
.Lkv_mapd:
	v_mov_b64_e32 v[0:1], 0x200
	v_cmp_lt_i64_e64 s[4:5], s[26:27], v[0:1]
	v_mov_b64_e32 v[0:1], 0x1ff
	v_cmp_gt_i64_e32 vcc, s[26:27], v[0:1]
	s_cbranch_vccnz .LBB0_570
	s_ashr_i32 s16, s26, 31
	s_lshr_b32 s16, s16, 29
	s_add_i32 s16, s26, s16
	s_and_b32 s17, s16, -8
	s_sub_i32 s17, s26, s17
	s_cmp_gt_i32 s17, -1
	s_mov_b64 s[52:53], -1
	s_cbranch_scc0 .LBB0_567
	s_lshl_b32 s54, s17, 6
	s_mov_b64 s[52:53], 0
